# PV: in-proj GEMM on pairs of M-tiles (256x128 per workgroup) sharing B fragments; A tiles single-buffered with early release, B double-buffered; 6 DMA pieces per 16 MFMAs
# speedup vs baseline: 1.0259x; 1.0190x over previous
.LBB0_173:
	s_or_b64 exec, exec, s[6:7]
	s_bitcmp1_b32 s0, 0
	s_cbranch_scc1 .Lpv_done
	s_add_i32 s0, s0, 1
	v_mov_b32_e32 v18, v104
	v_mov_b32_e32 v19, v105
	v_mov_b32_e32 v20, v106
	v_mov_b32_e32 v21, v107
	v_mov_b32_e32 v22, v108
	v_mov_b32_e32 v23, v109
	v_mov_b32_e32 v24, v110
	v_mov_b32_e32 v25, v111
	v_mov_b32_e32 v26, v112
	v_mov_b32_e32 v27, v113
	v_mov_b32_e32 v28, v114
	v_mov_b32_e32 v29, v115
	v_mov_b32_e32 v30, v116
	v_mov_b32_e32 v31, v117
	v_mov_b32_e32 v32, v118
	v_mov_b32_e32 v33, v119
	v_mov_b32_e32 v50, v128
	v_mov_b32_e32 v51, v129
	v_mov_b32_e32 v52, v130
	v_mov_b32_e32 v53, v131
	v_mov_b32_e32 v54, v132
	v_mov_b32_e32 v55, v133
	v_mov_b32_e32 v56, v134
	v_mov_b32_e32 v57, v135
	v_mov_b32_e32 v58, v136
	v_mov_b32_e32 v59, v137
	v_mov_b32_e32 v60, v138
	v_mov_b32_e32 v61, v139
	v_mov_b32_e32 v62, v140
	v_mov_b32_e32 v63, v141
	v_mov_b32_e32 v64, v142
	v_mov_b32_e32 v65, v143
	v_mov_b32_e32 v2, v196
	v_mov_b32_e32 v3, v197
	v_mov_b32_e32 v4, v198
	v_mov_b32_e32 v5, v199
	v_mov_b32_e32 v6, v200
	v_mov_b32_e32 v7, v201
	v_mov_b32_e32 v8, v202
	v_mov_b32_e32 v9, v203
	v_mov_b32_e32 v10, v204
	v_mov_b32_e32 v11, v205
	v_mov_b32_e32 v12, v206
	v_mov_b32_e32 v13, v207
	v_mov_b32_e32 v14, v208
	v_mov_b32_e32 v15, v209
	v_mov_b32_e32 v16, v210
	v_mov_b32_e32 v17, v211
	v_mov_b32_e32 v34, v236
	v_mov_b32_e32 v35, v237
	v_mov_b32_e32 v36, v238
	v_mov_b32_e32 v37, v239
	v_mov_b32_e32 v38, v240
	v_mov_b32_e32 v39, v241
	v_mov_b32_e32 v40, v242
	v_mov_b32_e32 v41, v243
	v_mov_b32_e32 v42, v244
	v_mov_b32_e32 v43, v245
	v_mov_b32_e32 v44, v246
	v_mov_b32_e32 v45, v247
	v_mov_b32_e32 v46, v248
	v_mov_b32_e32 v47, v249
	v_mov_b32_e32 v48, v250
	v_mov_b32_e32 v49, v251
	s_branch .LBB0_187
.Lpv_done:
	s_add_i32 s24, s24, 1
	s_mov_b64 s[4:5], 0

.LBB0_180:
	s_mul_i32 s0, s24, s51
	s_add_i32 s0, s0, s50
	s_cmpk_gt_u32 s0, 0xf7
	s_mov_b64 s[4:5], 0
	s_cbranch_scc1 .LBB0_182
	s_cmpk_gt_u32 s0, 0x7b
	s_cselect_b32 s1, 0xffffff84, 0
	s_cselect_b32 s4, 8, 0
	s_add_i32 s5, s1, s0
	s_and_b32 s0, s5, 3
	s_lshl_b32 s0, s0, 1
	s_or_b32 s0, s0, s4
	s_or_b32 s1, s0, s52
	s_ashr_i32 s8, s5, 2
	s_mov_b64 s[4:5], -1

.LBB0_183:
	s_ashr_i32 s1, s0, 31
	s_lshl_b64 s[4:5], s[0:1], 18
	s_add_u32 s8, s48, s4
	s_addc_u32 s9, s49, s5
	s_ashr_i32 s45, s44, 31
	s_lshl_b64 s[6:7], s[44:45], 18
	v_mov_b32_e32 v38, v156
	s_add_u32 s10, s22, s6
	s_addc_u32 s11, s23, s7
	v_readfirstlane_b32 s12, v38
	s_ashr_i32 s1, s12, 6
	v_bfe_u32 v0, v38, 3, 3
	v_lshl_or_b32 v2, s1, 5, v0
	v_min_i32_e32 v4, 0x7f, v2
	v_or_b32_e32 v10, 8, v2
	v_or_b32_e32 v20, 16, v2
	v_or_b32_e32 v28, 24, v2
	v_ashrrev_i32_e32 v5, 31, v4
	v_lshrrev_b32_e32 v11, 1, v10
	v_min_i32_e32 v12, 0x7f, v10
	v_min_i32_e32 v22, 0x7f, v20
	v_min_i32_e32 v30, 0x7f, v28
	v_lshlrev_b64 v[4:5], 11, v[4:5]
	v_lshlrev_b32_e32 v0, 4, v38
	v_and_b32_e32 v40, 48, v38
	v_ashrrev_i32_e32 v3, 31, v2
	v_xor_b32_e32 v11, v11, v38
	v_ashrrev_i32_e32 v13, 31, v12
	v_ashrrev_i32_e32 v23, 31, v22
	v_ashrrev_i32_e32 v31, 31, v30
	v_lshl_add_u64 v[4:5], s[8:9], 0, v[4:5]
	v_and_b32_e32 v41, 0x70, v0
	v_bitop3_b32 v0, v0, v40, s19 bitop3:0x6c
	v_lshlrev_b64 v[6:7], 11, v[2:3]
	v_lshlrev_b64 v[12:13], 11, v[12:13]
	v_lshlrev_b32_e32 v11, 4, v11
	v_lshlrev_b64 v[22:23], 11, v[22:23]
	v_lshrrev_b32_e32 v29, 1, v28
	v_lshlrev_b64 v[30:31], 11, v[30:31]
	s_lshl_b32 s1, s1, 12
	v_lshl_add_u64 v[4:5], v[4:5], 0, v[0:1]
	v_lshl_add_u64 v[8:9], s[10:11], 0, v[6:7]
	v_lshl_add_u64 v[12:13], s[8:9], 0, v[12:13]
	v_and_b32_e32 v14, 0x70, v11
	v_ashrrev_i32_e32 v11, 31, v10
	v_lshl_add_u64 v[22:23], s[8:9], 0, v[22:23]
	v_xor_b32_e32 v29, v29, v38
	v_lshl_add_u64 v[30:31], s[8:9], 0, v[30:31]
	s_add_i32 s8, s1, 0x4000
	s_mov_b32 m0, s1
	v_lshl_add_u64 v[8:9], v[8:9], 0, v[0:1]
	v_mov_b32_e32 v15, v1
	v_lshlrev_b64 v[16:17], 11, v[10:11]
	v_lshlrev_b32_e32 v29, 4, v29
	s_barrier
	global_load_lds_dwordx4 v[4:5], off
	s_mov_b32 m0, s8
	v_lshl_add_u64 v[12:13], v[12:13], 0, v[14:15]
	v_lshl_add_u64 v[18:19], s[10:11], 0, v[16:17]
	v_ashrrev_i32_e32 v21, 31, v20
	v_and_b32_e32 v32, 0x70, v29
	v_ashrrev_i32_e32 v29, 31, v28
	global_load_lds_dwordx4 v[8:9], off
	s_or_b32 m0, s1, 0x400
	s_add_i32 s9, s1, 0x4400
	v_lshl_add_u64 v[18:19], v[18:19], 0, v[14:15]
	v_lshlrev_b64 v[24:25], 11, v[20:21]
	v_lshlrev_b64 v[34:35], 11, v[28:29]
	global_load_lds_dwordx4 v[12:13], off
	s_mov_b32 m0, s9
	v_lshl_add_u64 v[22:23], v[22:23], 0, v[0:1]
	v_lshl_add_u64 v[26:27], s[10:11], 0, v[24:25]
	v_lshl_add_u64 v[36:37], s[10:11], 0, v[34:35]
	global_load_lds_dwordx4 v[18:19], off
	s_or_b32 m0, s1, 0x800
	s_add_i32 s10, s1, 0x4800
	v_lshl_add_u64 v[26:27], v[26:27], 0, v[0:1]
	v_mov_b32_e32 v33, v1
	global_load_lds_dwordx4 v[22:23], off
	s_mov_b32 m0, s10
	v_lshl_add_u64 v[30:31], v[30:31], 0, v[32:33]
	global_load_lds_dwordx4 v[26:27], off
	s_or_b32 m0, s1, 0xc00
	s_add_i32 s11, s1, 0x4c00
	v_lshl_add_u64 v[36:37], v[36:37], 0, v[32:33]
	global_load_lds_dwordx4 v[30:31], off
	s_mov_b32 m0, s11
	s_lshr_b32 s13, s12, 1
	global_load_lds_dwordx4 v[36:37], off
	v_and_b32_e32 v39, 31, v38
	s_and_b32 s13, s13, 0x1ffffc0
	v_or_b32_e32 v9, s13, v39
	v_cmp_gt_i64_e32 vcc, s[30:31], v[2:3]
	s_mul_i32 s13, s2, 0x7c0000
	s_add_u32 s6, s13, s6
	v_cndmask_b32_e32 v3, 0, v3, vcc
	v_cndmask_b32_e32 v2, v164, v2, vcc
	s_mul_hi_u32 s13, s2, 0x7c0000
	v_lshlrev_b64 v[2:3], 11, v[2:3]
	s_addc_u32 s7, s13, s7
	v_lshl_add_u64 v[66:67], s[4:5], 0, v[2:3]
	v_lshl_add_u64 v[2:3], s[6:7], 0, v[6:7]
	v_cmp_gt_i64_e32 vcc, s[30:31], v[10:11]
	v_lshl_add_u64 v[68:69], v[2:3], 0, v[0:1]
	v_bfe_u32 v4, v38, 5, 1
	v_cndmask_b32_e32 v3, 0, v11, vcc
	v_cndmask_b32_e32 v2, v164, v10, vcc
	v_lshlrev_b64 v[2:3], 11, v[2:3]
	v_lshrrev_b32_e32 v5, 1, v38
	v_lshl_add_u64 v[70:71], s[4:5], 0, v[2:3]
	v_lshl_add_u64 v[2:3], s[6:7], 0, v[16:17]
	v_cmp_gt_i64_e32 vcc, s[30:31], v[20:21]
	v_and_or_b32 v12, s12, 64, v39
	v_bitop3_b32 v5, v4, v5, 7 bitop3:0x78
	v_lshl_add_u64 v[72:73], v[2:3], 0, v[14:15]
	v_cndmask_b32_e32 v3, 0, v21, vcc
	v_cndmask_b32_e32 v2, v164, v20, vcc
	v_bfe_u32 v8, v38, 1, 3
	v_lshlrev_b32_e32 v9, 7, v9
	v_lshl_or_b32 v12, v12, 7, v163
	v_lshlrev_b32_e32 v5, 4, v5
	v_lshlrev_b64 v[2:3], 11, v[2:3]
	v_or_b32_e32 v84, v9, v5
	v_or_b32_e32 v85, v12, v5
	v_bitop3_b32 v5, v4, v8, 2 bitop3:0x36
	v_lshl_add_u64 v[74:75], s[4:5], 0, v[2:3]
	v_lshl_add_u64 v[2:3], s[6:7], 0, v[24:25]
	v_cmp_gt_i64_e32 vcc, s[30:31], v[28:29]
	v_lshlrev_b32_e32 v5, 4, v5
	v_lshl_add_u64 v[76:77], v[2:3], 0, v[0:1]
	v_cndmask_b32_e32 v3, 0, v29, vcc
	v_cndmask_b32_e32 v2, v164, v28, vcc
	s_waitcnt vmcnt(0)
	v_or_b32_e32 v86, v9, v5
	v_or_b32_e32 v87, v12, v5
	v_bitop3_b32 v5, v4, v8, 4 bitop3:0x36
	v_bitop3_b32 v4, v4, v8, 6 bitop3:0x36
	v_lshlrev_b64 v[2:3], 11, v[2:3]
	v_lshlrev_b32_e32 v5, 4, v5
	v_lshlrev_b32_e32 v4, 4, v4
	v_lshl_add_u64 v[78:79], s[4:5], 0, v[2:3]
	v_lshl_add_u64 v[2:3], s[6:7], 0, v[34:35]
	v_mov_b32_e32 v34, 0
	v_or_b32_e32 v88, v9, v5
	v_or_b32_e32 v89, v12, v5
	v_or_b32_e32 v90, v9, v4
	v_or_b32_e32 v91, v12, v4
	s_mov_b32 s12, 0
	v_bitop3_b32 v66, v66, v41, v40 bitop3:0xf6
	v_or_b32_e32 v70, v70, v14
	v_bitop3_b32 v74, v74, v41, v40 bitop3:0xf6
	v_or_b32_e32 v78, v78, v32
	v_lshl_add_u64 v[80:81], v[2:3], 0, v[32:33]
	s_add_i32 s6, s1, 0x8000
	s_add_i32 s7, s1, 0xc000
	s_add_i32 s13, s1, 0x8400
	s_add_i32 s14, s1, 0xc400
	s_add_i32 s15, s1, 0x8800
	s_add_i32 s16, s1, 0xc800
	s_add_i32 s17, s1, 0x8c00
	s_add_i32 s25, s1, 0xcc00
	v_mov_b32_e32 v35, v34
	v_mov_b32_e32 v36, v34
	v_mov_b32_e32 v37, v34
	v_mov_b32_e32 v38, v34
	v_mov_b32_e32 v39, v34
	v_mov_b32_e32 v40, v34
	v_mov_b32_e32 v41, v34
	v_mov_b32_e32 v42, v34
	v_mov_b32_e32 v43, v34
	v_mov_b32_e32 v44, v34
	v_mov_b32_e32 v45, v34
	v_mov_b32_e32 v46, v34
	v_mov_b32_e32 v47, v34
	v_mov_b32_e32 v48, v34
	v_mov_b32_e32 v49, v34
	v_mov_b32_e32 v2, v34
	v_mov_b32_e32 v3, v34
	v_mov_b32_e32 v4, v34
	v_mov_b32_e32 v5, v34
	v_mov_b32_e32 v6, v34
	v_mov_b32_e32 v7, v34
	v_mov_b32_e32 v8, v34
	v_mov_b32_e32 v9, v34
	v_mov_b32_e32 v10, v34
	v_mov_b32_e32 v11, v34
	v_mov_b32_e32 v12, v34
	v_mov_b32_e32 v13, v34
	v_mov_b32_e32 v14, v34
	v_mov_b32_e32 v15, v34
	v_mov_b32_e32 v16, v34
	v_mov_b32_e32 v17, v34
	v_mov_b32_e32 v50, v34
	v_mov_b32_e32 v51, v34
	v_mov_b32_e32 v52, v34
	v_mov_b32_e32 v53, v34
	v_mov_b32_e32 v54, v34
	v_mov_b32_e32 v55, v34
	v_mov_b32_e32 v56, v34
	v_mov_b32_e32 v57, v34
	v_mov_b32_e32 v58, v34
	v_mov_b32_e32 v59, v34
	v_mov_b32_e32 v60, v34
	v_mov_b32_e32 v61, v34
	v_mov_b32_e32 v62, v34
	v_mov_b32_e32 v63, v34
	v_mov_b32_e32 v64, v34
	v_mov_b32_e32 v65, v34
	v_mov_b32_e32 v18, v34
	v_mov_b32_e32 v19, v34
	v_mov_b32_e32 v20, v34
	v_mov_b32_e32 v21, v34
	v_mov_b32_e32 v22, v34
	v_mov_b32_e32 v23, v34
	v_mov_b32_e32 v24, v34
	v_mov_b32_e32 v25, v34
	v_mov_b32_e32 v26, v34
	v_mov_b32_e32 v27, v34
	v_mov_b32_e32 v28, v34
	v_mov_b32_e32 v29, v34
	v_mov_b32_e32 v30, v34
	v_mov_b32_e32 v31, v34
	v_mov_b32_e32 v32, v34
	v_mov_b32_e32 v33, v34
	s_waitcnt vmcnt(0) lgkmcnt(0)
	s_barrier
	v_lshl_add_u64 v[66:67], s[80:81], 0, v[66:67]
	v_lshl_add_u64 v[66:67], v[66:67], 0, s[64:65]
	v_lshl_add_u64 v[68:69], s[80:81], 0, v[68:69]
	v_lshl_add_u64 v[68:69], v[68:69], 0, s[66:67]
	v_lshl_add_u64 v[70:71], s[80:81], 0, v[70:71]
	v_lshl_add_u64 v[70:71], v[70:71], 0, s[64:65]
	v_lshl_add_u64 v[72:73], s[80:81], 0, v[72:73]
	v_lshl_add_u64 v[72:73], v[72:73], 0, s[66:67]
	v_lshl_add_u64 v[74:75], s[80:81], 0, v[74:75]
	v_lshl_add_u64 v[74:75], v[74:75], 0, s[64:65]
	v_lshl_add_u64 v[76:77], s[80:81], 0, v[76:77]
	v_lshl_add_u64 v[76:77], v[76:77], 0, s[66:67]
	v_lshl_add_u64 v[78:79], s[80:81], 0, v[78:79]
	v_lshl_add_u64 v[78:79], v[78:79], 0, s[64:65]
	v_lshl_add_u64 v[80:81], s[80:81], 0, v[80:81]
	v_lshl_add_u64 v[80:81], v[80:81], 0, s[66:67]
	s_mov_b64 s[26:27], 0x40000
	s_mov_b64 s[72:73], 0x3ff80
	s_mov_b32 m0, s6
	v_lshl_add_u64 v[82:83], v[66:67], 0, s[72:73]
	s_nop 0
	global_load_lds_dwordx4 v[82:83], off
	s_mov_b32 m0, s13
	v_lshl_add_u64 v[82:83], v[70:71], 0, s[72:73]
	s_nop 0
	global_load_lds_dwordx4 v[82:83], off
	s_mov_b32 m0, s15
	v_lshl_add_u64 v[82:83], v[74:75], 0, s[72:73]
	s_nop 0
	global_load_lds_dwordx4 v[82:83], off
	s_mov_b32 m0, s17
	v_lshl_add_u64 v[82:83], v[78:79], 0, s[72:73]
	s_nop 0
	global_load_lds_dwordx4 v[82:83], off
	s_mov_b32 m0, s7
	s_nop 0
	global_load_lds_dwordx4 v[68:69], off
	v_lshl_add_u64 v[68:69], v[68:69], 0, s[34:35]
	s_mov_b32 m0, s14
	s_nop 0
	global_load_lds_dwordx4 v[72:73], off
	v_lshl_add_u64 v[72:73], v[72:73], 0, s[34:35]
	s_mov_b32 m0, s16
	s_nop 0
	global_load_lds_dwordx4 v[76:77], off
	v_lshl_add_u64 v[76:77], v[76:77], 0, s[34:35]
	s_mov_b32 m0, s25
	s_nop 0
	global_load_lds_dwordx4 v[80:81], off
	v_lshl_add_u64 v[80:81], v[80:81], 0, s[34:35]
	v_mov_b32_e32 v104, 0
	v_mov_b32_e32 v105, 0
	v_mov_b32_e32 v106, 0
	v_mov_b32_e32 v107, 0
	v_mov_b32_e32 v108, 0
	v_mov_b32_e32 v109, 0
	v_mov_b32_e32 v110, 0
	v_mov_b32_e32 v111, 0
	v_mov_b32_e32 v112, 0
	v_mov_b32_e32 v113, 0
	v_mov_b32_e32 v114, 0
	v_mov_b32_e32 v115, 0
	v_mov_b32_e32 v116, 0
	v_mov_b32_e32 v117, 0
	v_mov_b32_e32 v118, 0
	v_mov_b32_e32 v119, 0
	v_mov_b32_e32 v128, 0
	v_mov_b32_e32 v129, 0
	v_mov_b32_e32 v130, 0
	v_mov_b32_e32 v131, 0
	v_mov_b32_e32 v132, 0
	v_mov_b32_e32 v133, 0
	v_mov_b32_e32 v134, 0
	v_mov_b32_e32 v135, 0
	v_mov_b32_e32 v136, 0
	v_mov_b32_e32 v137, 0
	v_mov_b32_e32 v138, 0
	v_mov_b32_e32 v139, 0
	v_mov_b32_e32 v140, 0
	v_mov_b32_e32 v141, 0
	v_mov_b32_e32 v142, 0
	v_mov_b32_e32 v143, 0
	v_mov_b32_e32 v196, 0
	v_mov_b32_e32 v197, 0
	v_mov_b32_e32 v198, 0
	v_mov_b32_e32 v199, 0
	v_mov_b32_e32 v200, 0
	v_mov_b32_e32 v201, 0
	v_mov_b32_e32 v202, 0
	v_mov_b32_e32 v203, 0
	v_mov_b32_e32 v204, 0
	v_mov_b32_e32 v205, 0
	v_mov_b32_e32 v206, 0
	v_mov_b32_e32 v207, 0
	v_mov_b32_e32 v208, 0
	v_mov_b32_e32 v209, 0
	v_mov_b32_e32 v210, 0
	v_mov_b32_e32 v211, 0
	v_mov_b32_e32 v236, 0
	v_mov_b32_e32 v237, 0
	v_mov_b32_e32 v238, 0
	v_mov_b32_e32 v239, 0
	v_mov_b32_e32 v240, 0
	v_mov_b32_e32 v241, 0
	v_mov_b32_e32 v242, 0
	v_mov_b32_e32 v243, 0
	v_mov_b32_e32 v244, 0
	v_mov_b32_e32 v245, 0
	v_mov_b32_e32 v246, 0
	v_mov_b32_e32 v247, 0
	v_mov_b32_e32 v248, 0
	v_mov_b32_e32 v249, 0
	v_mov_b32_e32 v250, 0
	v_mov_b32_e32 v251, 0
	s_mov_b32 s12, 0
.Lg1_loop:
	ds_read_b128 v[92:95], v84 offset:0
	ds_read_b128 v[96:99], v84 offset:4096
	ds_read_b128 v[188:191], v85 offset:0
	ds_read_b128 v[192:195], v85 offset:4096
	ds_read_b128 v[100:103], v86 offset:0
	ds_read_b128 v[144:147], v86 offset:4096
	ds_read_b128 v[212:215], v87 offset:0
	ds_read_b128 v[216:219], v87 offset:4096
	ds_read_b128 v[148:151], v88 offset:0
	ds_read_b128 v[152:155], v88 offset:4096
	ds_read_b128 v[220:223], v89 offset:0
	ds_read_b128 v[224:227], v89 offset:4096
	ds_read_b128 v[180:183], v90 offset:0
	ds_read_b128 v[184:187], v90 offset:4096
	ds_read_b128 v[228:231], v91 offset:0
	ds_read_b128 v[252:255], v91 offset:4096
	s_waitcnt lgkmcnt(0)
	s_barrier
	s_mov_b32 m0, s1
	v_mfma_f32_32x32x16_bf16 v[18:33], v[92:95], v[188:191], v[18:33]
	global_load_lds_dwordx4 v[66:67], off
	v_mfma_f32_32x32x16_bf16 v[50:65], v[92:95], v[192:195], v[50:65]
	s_add_i32 m0, s1, 0x400
	v_mfma_f32_32x32x16_bf16 v[2:17], v[96:99], v[188:191], v[2:17]
	global_load_lds_dwordx4 v[70:71], off
	v_mfma_f32_32x32x16_bf16 v[34:49], v[96:99], v[192:195], v[34:49]
	s_add_i32 m0, s1, 0x800
	v_mfma_f32_32x32x16_bf16 v[18:33], v[100:103], v[212:215], v[18:33]
	global_load_lds_dwordx4 v[74:75], off
	v_mfma_f32_32x32x16_bf16 v[50:65], v[100:103], v[216:219], v[50:65]
	s_add_i32 m0, s1, 0xc00
	v_mfma_f32_32x32x16_bf16 v[2:17], v[144:147], v[212:215], v[2:17]
	global_load_lds_dwordx4 v[78:79], off
	v_mfma_f32_32x32x16_bf16 v[34:49], v[144:147], v[216:219], v[34:49]
	s_mov_b32 m0, s8
	v_mfma_f32_32x32x16_bf16 v[18:33], v[148:151], v[220:223], v[18:33]
	global_load_lds_dwordx4 v[68:69], off
	v_lshl_add_u64 v[68:69], v[68:69], 0, s[34:35]
	v_mfma_f32_32x32x16_bf16 v[50:65], v[148:151], v[224:227], v[50:65]
	s_mov_b32 m0, s9
	v_mfma_f32_32x32x16_bf16 v[2:17], v[152:155], v[220:223], v[2:17]
	global_load_lds_dwordx4 v[72:73], off
	v_lshl_add_u64 v[72:73], v[72:73], 0, s[34:35]
	v_mfma_f32_32x32x16_bf16 v[34:49], v[152:155], v[224:227], v[34:49]
	v_mfma_f32_32x32x16_bf16 v[18:33], v[180:183], v[228:231], v[18:33]
	v_mfma_f32_32x32x16_bf16 v[50:65], v[180:183], v[252:255], v[50:65]
	v_mfma_f32_32x32x16_bf16 v[2:17], v[184:187], v[228:231], v[2:17]
	v_mfma_f32_32x32x16_bf16 v[34:49], v[184:187], v[252:255], v[34:49]
	s_waitcnt vmcnt(6)
	s_barrier
	ds_read_b128 v[92:95], v84 offset:32768
	ds_read_b128 v[96:99], v84 offset:36864
	ds_read_b128 v[100:103], v86 offset:32768
	ds_read_b128 v[144:147], v86 offset:36864
	ds_read_b128 v[148:151], v88 offset:32768
	ds_read_b128 v[152:155], v88 offset:36864
	ds_read_b128 v[180:183], v90 offset:32768
	ds_read_b128 v[184:187], v90 offset:36864
	s_waitcnt lgkmcnt(0)
	s_barrier
	s_mov_b32 m0, s6
	v_lshl_add_u64 v[82:83], v[66:67], 0, s[26:27]
	v_mfma_f32_32x32x16_bf16 v[104:119], v[92:95], v[188:191], v[104:119]
	global_load_lds_dwordx4 v[82:83], off
	v_lshl_add_u64 v[66:67], v[66:67], 0, s[34:35]
	v_mfma_f32_32x32x16_bf16 v[128:143], v[92:95], v[192:195], v[128:143]
	s_mov_b32 m0, s13
	v_lshl_add_u64 v[82:83], v[70:71], 0, s[26:27]
	v_mfma_f32_32x32x16_bf16 v[196:211], v[96:99], v[188:191], v[196:211]
	global_load_lds_dwordx4 v[82:83], off
	v_lshl_add_u64 v[70:71], v[70:71], 0, s[34:35]
	v_mfma_f32_32x32x16_bf16 v[236:251], v[96:99], v[192:195], v[236:251]
	s_mov_b32 m0, s15
	v_lshl_add_u64 v[82:83], v[74:75], 0, s[26:27]
	v_mfma_f32_32x32x16_bf16 v[104:119], v[100:103], v[212:215], v[104:119]
	global_load_lds_dwordx4 v[82:83], off
	v_lshl_add_u64 v[74:75], v[74:75], 0, s[34:35]
	v_mfma_f32_32x32x16_bf16 v[128:143], v[100:103], v[216:219], v[128:143]
	s_mov_b32 m0, s17
	v_lshl_add_u64 v[82:83], v[78:79], 0, s[26:27]
	v_mfma_f32_32x32x16_bf16 v[196:211], v[144:147], v[212:215], v[196:211]
	global_load_lds_dwordx4 v[82:83], off
	v_lshl_add_u64 v[78:79], v[78:79], 0, s[34:35]
	v_mfma_f32_32x32x16_bf16 v[236:251], v[144:147], v[216:219], v[236:251]
	s_mov_b32 m0, s10
	v_mfma_f32_32x32x16_bf16 v[104:119], v[148:151], v[220:223], v[104:119]
	global_load_lds_dwordx4 v[76:77], off
	v_lshl_add_u64 v[76:77], v[76:77], 0, s[34:35]
	v_mfma_f32_32x32x16_bf16 v[128:143], v[148:151], v[224:227], v[128:143]
	s_mov_b32 m0, s11
	v_mfma_f32_32x32x16_bf16 v[196:211], v[152:155], v[220:223], v[196:211]
	global_load_lds_dwordx4 v[80:81], off
	v_lshl_add_u64 v[80:81], v[80:81], 0, s[34:35]
	v_mfma_f32_32x32x16_bf16 v[236:251], v[152:155], v[224:227], v[236:251]
	v_mfma_f32_32x32x16_bf16 v[104:119], v[180:183], v[228:231], v[104:119]
	v_mfma_f32_32x32x16_bf16 v[128:143], v[180:183], v[252:255], v[128:143]
	v_mfma_f32_32x32x16_bf16 v[196:211], v[184:187], v[228:231], v[196:211]
	v_mfma_f32_32x32x16_bf16 v[236:251], v[184:187], v[252:255], v[236:251]
	s_waitcnt vmcnt(6)
	s_barrier
	ds_read_b128 v[92:95], v84 offset:0
	ds_read_b128 v[96:99], v84 offset:4096
	ds_read_b128 v[188:191], v85 offset:32768
	ds_read_b128 v[192:195], v85 offset:36864
	ds_read_b128 v[100:103], v86 offset:0
	ds_read_b128 v[144:147], v86 offset:4096
	ds_read_b128 v[212:215], v87 offset:32768
	ds_read_b128 v[216:219], v87 offset:36864
	ds_read_b128 v[148:151], v88 offset:0
	ds_read_b128 v[152:155], v88 offset:4096
	ds_read_b128 v[220:223], v89 offset:32768
	ds_read_b128 v[224:227], v89 offset:36864
	ds_read_b128 v[180:183], v90 offset:0
	ds_read_b128 v[184:187], v90 offset:4096
	ds_read_b128 v[228:231], v91 offset:32768
	ds_read_b128 v[252:255], v91 offset:36864
	s_waitcnt lgkmcnt(0)
	s_barrier
	s_mov_b32 m0, s1
	v_mfma_f32_32x32x16_bf16 v[18:33], v[92:95], v[188:191], v[18:33]
	global_load_lds_dwordx4 v[66:67], off
	v_mfma_f32_32x32x16_bf16 v[50:65], v[92:95], v[192:195], v[50:65]
	s_add_i32 m0, s1, 0x400
	v_mfma_f32_32x32x16_bf16 v[2:17], v[96:99], v[188:191], v[2:17]
	global_load_lds_dwordx4 v[70:71], off
	v_mfma_f32_32x32x16_bf16 v[34:49], v[96:99], v[192:195], v[34:49]
	s_add_i32 m0, s1, 0x800
	v_mfma_f32_32x32x16_bf16 v[18:33], v[100:103], v[212:215], v[18:33]
	global_load_lds_dwordx4 v[74:75], off
	v_mfma_f32_32x32x16_bf16 v[50:65], v[100:103], v[216:219], v[50:65]
	s_add_i32 m0, s1, 0xc00
	v_mfma_f32_32x32x16_bf16 v[2:17], v[144:147], v[212:215], v[2:17]
	global_load_lds_dwordx4 v[78:79], off
	v_mfma_f32_32x32x16_bf16 v[34:49], v[144:147], v[216:219], v[34:49]
	s_mov_b32 m0, s7
	v_mfma_f32_32x32x16_bf16 v[18:33], v[148:151], v[220:223], v[18:33]
	global_load_lds_dwordx4 v[68:69], off
	v_lshl_add_u64 v[68:69], v[68:69], 0, s[34:35]
	v_mfma_f32_32x32x16_bf16 v[50:65], v[148:151], v[224:227], v[50:65]
	s_mov_b32 m0, s14
	v_mfma_f32_32x32x16_bf16 v[2:17], v[152:155], v[220:223], v[2:17]
	global_load_lds_dwordx4 v[72:73], off
	v_lshl_add_u64 v[72:73], v[72:73], 0, s[34:35]
	v_mfma_f32_32x32x16_bf16 v[34:49], v[152:155], v[224:227], v[34:49]
	v_mfma_f32_32x32x16_bf16 v[18:33], v[180:183], v[228:231], v[18:33]
	v_mfma_f32_32x32x16_bf16 v[50:65], v[180:183], v[252:255], v[50:65]
	v_mfma_f32_32x32x16_bf16 v[2:17], v[184:187], v[228:231], v[2:17]
	v_mfma_f32_32x32x16_bf16 v[34:49], v[184:187], v[252:255], v[34:49]
	s_waitcnt vmcnt(6)
	s_barrier
	ds_read_b128 v[92:95], v84 offset:32768
	ds_read_b128 v[96:99], v84 offset:36864
	ds_read_b128 v[100:103], v86 offset:32768
	ds_read_b128 v[144:147], v86 offset:36864
	ds_read_b128 v[148:151], v88 offset:32768
	ds_read_b128 v[152:155], v88 offset:36864
	ds_read_b128 v[180:183], v90 offset:32768
	ds_read_b128 v[184:187], v90 offset:36864
	s_waitcnt lgkmcnt(0)
	s_barrier
	s_mov_b32 m0, s6
	v_lshl_add_u64 v[82:83], v[66:67], 0, s[26:27]
	v_mfma_f32_32x32x16_bf16 v[104:119], v[92:95], v[188:191], v[104:119]
	global_load_lds_dwordx4 v[82:83], off
	v_lshl_add_u64 v[66:67], v[66:67], 0, s[34:35]
	v_mfma_f32_32x32x16_bf16 v[128:143], v[92:95], v[192:195], v[128:143]
	s_mov_b32 m0, s13
	v_lshl_add_u64 v[82:83], v[70:71], 0, s[26:27]
	v_mfma_f32_32x32x16_bf16 v[196:211], v[96:99], v[188:191], v[196:211]
	global_load_lds_dwordx4 v[82:83], off
	v_lshl_add_u64 v[70:71], v[70:71], 0, s[34:35]
	v_mfma_f32_32x32x16_bf16 v[236:251], v[96:99], v[192:195], v[236:251]
	s_mov_b32 m0, s15
	v_lshl_add_u64 v[82:83], v[74:75], 0, s[26:27]
	v_mfma_f32_32x32x16_bf16 v[104:119], v[100:103], v[212:215], v[104:119]
	global_load_lds_dwordx4 v[82:83], off
	v_lshl_add_u64 v[74:75], v[74:75], 0, s[34:35]
	v_mfma_f32_32x32x16_bf16 v[128:143], v[100:103], v[216:219], v[128:143]
	s_mov_b32 m0, s17
	v_lshl_add_u64 v[82:83], v[78:79], 0, s[26:27]
	v_mfma_f32_32x32x16_bf16 v[196:211], v[144:147], v[212:215], v[196:211]
	global_load_lds_dwordx4 v[82:83], off
	v_lshl_add_u64 v[78:79], v[78:79], 0, s[34:35]
	v_mfma_f32_32x32x16_bf16 v[236:251], v[144:147], v[216:219], v[236:251]
	s_mov_b32 m0, s16
	v_mfma_f32_32x32x16_bf16 v[104:119], v[148:151], v[220:223], v[104:119]
	global_load_lds_dwordx4 v[76:77], off
	v_lshl_add_u64 v[76:77], v[76:77], 0, s[34:35]
	v_mfma_f32_32x32x16_bf16 v[128:143], v[148:151], v[224:227], v[128:143]
	s_mov_b32 m0, s25
	v_mfma_f32_32x32x16_bf16 v[196:211], v[152:155], v[220:223], v[196:211]
	global_load_lds_dwordx4 v[80:81], off
	v_lshl_add_u64 v[80:81], v[80:81], 0, s[34:35]
	v_mfma_f32_32x32x16_bf16 v[236:251], v[152:155], v[224:227], v[236:251]
	v_mfma_f32_32x32x16_bf16 v[104:119], v[180:183], v[228:231], v[104:119]
	v_mfma_f32_32x32x16_bf16 v[128:143], v[180:183], v[252:255], v[128:143]
	v_mfma_f32_32x32x16_bf16 v[196:211], v[184:187], v[228:231], v[196:211]
	v_mfma_f32_32x32x16_bf16 v[236:251], v[184:187], v[252:255], v[236:251]
	s_waitcnt vmcnt(6)
	s_barrier
	s_add_i32 s12, s12, 2
	s_cmp_lt_u32 s12, 14
	s_cbranch_scc1 .Lg1_loop
	ds_read_b128 v[92:95], v84 offset:0
	ds_read_b128 v[96:99], v84 offset:4096
	ds_read_b128 v[188:191], v85 offset:0
	ds_read_b128 v[192:195], v85 offset:4096
	ds_read_b128 v[100:103], v86 offset:0
	ds_read_b128 v[144:147], v86 offset:4096
	ds_read_b128 v[212:215], v87 offset:0
	ds_read_b128 v[216:219], v87 offset:4096
	ds_read_b128 v[148:151], v88 offset:0
	ds_read_b128 v[152:155], v88 offset:4096
	ds_read_b128 v[220:223], v89 offset:0
	ds_read_b128 v[224:227], v89 offset:4096
	ds_read_b128 v[180:183], v90 offset:0
	ds_read_b128 v[184:187], v90 offset:4096
	ds_read_b128 v[228:231], v91 offset:0
	ds_read_b128 v[252:255], v91 offset:4096
	s_waitcnt lgkmcnt(0)
	s_barrier
	s_mov_b32 m0, s1
	v_mfma_f32_32x32x16_bf16 v[18:33], v[92:95], v[188:191], v[18:33]
	global_load_lds_dwordx4 v[66:67], off
	v_mfma_f32_32x32x16_bf16 v[50:65], v[92:95], v[192:195], v[50:65]
	s_add_i32 m0, s1, 0x400
	v_mfma_f32_32x32x16_bf16 v[2:17], v[96:99], v[188:191], v[2:17]
	global_load_lds_dwordx4 v[70:71], off
	v_mfma_f32_32x32x16_bf16 v[34:49], v[96:99], v[192:195], v[34:49]
	s_add_i32 m0, s1, 0x800
	v_mfma_f32_32x32x16_bf16 v[18:33], v[100:103], v[212:215], v[18:33]
	global_load_lds_dwordx4 v[74:75], off
	v_mfma_f32_32x32x16_bf16 v[50:65], v[100:103], v[216:219], v[50:65]
	s_add_i32 m0, s1, 0xc00
	v_mfma_f32_32x32x16_bf16 v[2:17], v[144:147], v[212:215], v[2:17]
	global_load_lds_dwordx4 v[78:79], off
	v_mfma_f32_32x32x16_bf16 v[34:49], v[144:147], v[216:219], v[34:49]
	v_mfma_f32_32x32x16_bf16 v[18:33], v[148:151], v[220:223], v[18:33]
	v_mfma_f32_32x32x16_bf16 v[50:65], v[148:151], v[224:227], v[50:65]
	v_mfma_f32_32x32x16_bf16 v[2:17], v[152:155], v[220:223], v[2:17]
	v_mfma_f32_32x32x16_bf16 v[34:49], v[152:155], v[224:227], v[34:49]
	v_mfma_f32_32x32x16_bf16 v[18:33], v[180:183], v[228:231], v[18:33]
	v_mfma_f32_32x32x16_bf16 v[50:65], v[180:183], v[252:255], v[50:65]
	v_mfma_f32_32x32x16_bf16 v[2:17], v[184:187], v[228:231], v[2:17]
	v_mfma_f32_32x32x16_bf16 v[34:49], v[184:187], v[252:255], v[34:49]
	s_waitcnt vmcnt(4)
	s_barrier
	ds_read_b128 v[92:95], v84 offset:32768
	ds_read_b128 v[96:99], v84 offset:36864
	ds_read_b128 v[100:103], v86 offset:32768
	ds_read_b128 v[144:147], v86 offset:36864
	ds_read_b128 v[148:151], v88 offset:32768
	ds_read_b128 v[152:155], v88 offset:36864
	ds_read_b128 v[180:183], v90 offset:32768
	ds_read_b128 v[184:187], v90 offset:36864
	s_waitcnt lgkmcnt(0)
	s_barrier
	s_mov_b32 m0, s6
	v_lshl_add_u64 v[82:83], v[66:67], 0, s[26:27]
	v_mfma_f32_32x32x16_bf16 v[104:119], v[92:95], v[188:191], v[104:119]
	global_load_lds_dwordx4 v[82:83], off
	v_lshl_add_u64 v[66:67], v[66:67], 0, s[34:35]
	v_mfma_f32_32x32x16_bf16 v[128:143], v[92:95], v[192:195], v[128:143]
	s_mov_b32 m0, s13
	v_lshl_add_u64 v[82:83], v[70:71], 0, s[26:27]
	v_mfma_f32_32x32x16_bf16 v[196:211], v[96:99], v[188:191], v[196:211]
	global_load_lds_dwordx4 v[82:83], off
	v_lshl_add_u64 v[70:71], v[70:71], 0, s[34:35]
	v_mfma_f32_32x32x16_bf16 v[236:251], v[96:99], v[192:195], v[236:251]
	s_mov_b32 m0, s15
	v_lshl_add_u64 v[82:83], v[74:75], 0, s[26:27]
	v_mfma_f32_32x32x16_bf16 v[104:119], v[100:103], v[212:215], v[104:119]
	global_load_lds_dwordx4 v[82:83], off
	v_lshl_add_u64 v[74:75], v[74:75], 0, s[34:35]
	v_mfma_f32_32x32x16_bf16 v[128:143], v[100:103], v[216:219], v[128:143]
	s_mov_b32 m0, s17
	v_lshl_add_u64 v[82:83], v[78:79], 0, s[26:27]
	v_mfma_f32_32x32x16_bf16 v[196:211], v[144:147], v[212:215], v[196:211]
	global_load_lds_dwordx4 v[82:83], off
	v_lshl_add_u64 v[78:79], v[78:79], 0, s[34:35]
	v_mfma_f32_32x32x16_bf16 v[236:251], v[144:147], v[216:219], v[236:251]
	v_mfma_f32_32x32x16_bf16 v[104:119], v[148:151], v[220:223], v[104:119]
	v_mfma_f32_32x32x16_bf16 v[128:143], v[148:151], v[224:227], v[128:143]
	v_mfma_f32_32x32x16_bf16 v[196:211], v[152:155], v[220:223], v[196:211]
	v_mfma_f32_32x32x16_bf16 v[236:251], v[152:155], v[224:227], v[236:251]
	v_mfma_f32_32x32x16_bf16 v[104:119], v[180:183], v[228:231], v[104:119]
	v_mfma_f32_32x32x16_bf16 v[128:143], v[180:183], v[252:255], v[128:143]
	v_mfma_f32_32x32x16_bf16 v[196:211], v[184:187], v[228:231], v[196:211]
	v_mfma_f32_32x32x16_bf16 v[236:251], v[184:187], v[252:255], v[236:251]
	s_waitcnt vmcnt(4)
	s_barrier
	ds_read_b128 v[92:95], v84 offset:0
	ds_read_b128 v[96:99], v84 offset:4096
	ds_read_b128 v[188:191], v85 offset:32768
	ds_read_b128 v[192:195], v85 offset:36864
	ds_read_b128 v[100:103], v86 offset:0
	ds_read_b128 v[144:147], v86 offset:4096
	ds_read_b128 v[212:215], v87 offset:32768
	ds_read_b128 v[216:219], v87 offset:36864
	ds_read_b128 v[148:151], v88 offset:0
	ds_read_b128 v[152:155], v88 offset:4096
	ds_read_b128 v[220:223], v89 offset:32768
	ds_read_b128 v[224:227], v89 offset:36864
	ds_read_b128 v[180:183], v90 offset:0
	ds_read_b128 v[184:187], v90 offset:4096
	ds_read_b128 v[228:231], v91 offset:32768
	ds_read_b128 v[252:255], v91 offset:36864
	s_waitcnt lgkmcnt(0)
	s_barrier
	v_mfma_f32_32x32x16_bf16 v[18:33], v[92:95], v[188:191], v[18:33]
	v_mfma_f32_32x32x16_bf16 v[50:65], v[92:95], v[192:195], v[50:65]
	v_mfma_f32_32x32x16_bf16 v[2:17], v[96:99], v[188:191], v[2:17]
	v_mfma_f32_32x32x16_bf16 v[34:49], v[96:99], v[192:195], v[34:49]
	v_mfma_f32_32x32x16_bf16 v[18:33], v[100:103], v[212:215], v[18:33]
	v_mfma_f32_32x32x16_bf16 v[50:65], v[100:103], v[216:219], v[50:65]
	v_mfma_f32_32x32x16_bf16 v[2:17], v[144:147], v[212:215], v[2:17]
	v_mfma_f32_32x32x16_bf16 v[34:49], v[144:147], v[216:219], v[34:49]
	v_mfma_f32_32x32x16_bf16 v[18:33], v[148:151], v[220:223], v[18:33]
	v_mfma_f32_32x32x16_bf16 v[50:65], v[148:151], v[224:227], v[50:65]
	v_mfma_f32_32x32x16_bf16 v[2:17], v[152:155], v[220:223], v[2:17]
	v_mfma_f32_32x32x16_bf16 v[34:49], v[152:155], v[224:227], v[34:49]
	v_mfma_f32_32x32x16_bf16 v[18:33], v[180:183], v[228:231], v[18:33]
	v_mfma_f32_32x32x16_bf16 v[50:65], v[180:183], v[252:255], v[50:65]
	v_mfma_f32_32x32x16_bf16 v[2:17], v[184:187], v[228:231], v[2:17]
	v_mfma_f32_32x32x16_bf16 v[34:49], v[184:187], v[252:255], v[34:49]
	s_waitcnt vmcnt(0)
	s_barrier
	ds_read_b128 v[92:95], v84 offset:32768
	ds_read_b128 v[96:99], v84 offset:36864
	ds_read_b128 v[100:103], v86 offset:32768
	ds_read_b128 v[144:147], v86 offset:36864
	ds_read_b128 v[148:151], v88 offset:32768
	ds_read_b128 v[152:155], v88 offset:36864
	ds_read_b128 v[180:183], v90 offset:32768
	ds_read_b128 v[184:187], v90 offset:36864
	s_waitcnt lgkmcnt(0)
	s_barrier
	v_mfma_f32_32x32x16_bf16 v[104:119], v[92:95], v[188:191], v[104:119]
	v_mfma_f32_32x32x16_bf16 v[128:143], v[92:95], v[192:195], v[128:143]
	v_mfma_f32_32x32x16_bf16 v[196:211], v[96:99], v[188:191], v[196:211]
	v_mfma_f32_32x32x16_bf16 v[236:251], v[96:99], v[192:195], v[236:251]
	v_mfma_f32_32x32x16_bf16 v[104:119], v[100:103], v[212:215], v[104:119]
	v_mfma_f32_32x32x16_bf16 v[128:143], v[100:103], v[216:219], v[128:143]
	v_mfma_f32_32x32x16_bf16 v[196:211], v[144:147], v[212:215], v[196:211]
	v_mfma_f32_32x32x16_bf16 v[236:251], v[144:147], v[216:219], v[236:251]
	v_mfma_f32_32x32x16_bf16 v[104:119], v[148:151], v[220:223], v[104:119]
	v_mfma_f32_32x32x16_bf16 v[128:143], v[148:151], v[224:227], v[128:143]
	v_mfma_f32_32x32x16_bf16 v[196:211], v[152:155], v[220:223], v[196:211]
	v_mfma_f32_32x32x16_bf16 v[236:251], v[152:155], v[224:227], v[236:251]
	v_mfma_f32_32x32x16_bf16 v[104:119], v[180:183], v[228:231], v[104:119]
	v_mfma_f32_32x32x16_bf16 v[128:143], v[180:183], v[252:255], v[128:143]
	v_mfma_f32_32x32x16_bf16 v[196:211], v[184:187], v[228:231], v[196:211]
	v_mfma_f32_32x32x16_bf16 v[236:251], v[184:187], v[252:255], v[236:251]
	s_waitcnt vmcnt(0) lgkmcnt(0)
	s_barrier

	.amdhsa_kernel _Z10fwd_kernel6Params
		.amdhsa_group_segment_fixed_size 73760
		.amdhsa_private_segment_fixed_size 0
		.amdhsa_kernarg_size 416
		.amdhsa_user_sgpr_count 2
		.amdhsa_user_sgpr_dispatch_ptr 0
		.amdhsa_user_sgpr_queue_ptr 0
		.amdhsa_user_sgpr_kernarg_segment_ptr 1
		.amdhsa_user_sgpr_dispatch_id 0
		.amdhsa_user_sgpr_kernarg_preload_length 0
		.amdhsa_user_sgpr_kernarg_preload_offset 0
		.amdhsa_user_sgpr_private_segment_size 0
		.amdhsa_uses_dynamic_stack 0
		.amdhsa_enable_private_segment 0
		.amdhsa_system_sgpr_workgroup_id_x 1
		.amdhsa_system_sgpr_workgroup_id_y 0
		.amdhsa_system_sgpr_workgroup_id_z 0
		.amdhsa_system_sgpr_workgroup_info 0
		.amdhsa_system_vgpr_workitem_id 2
		.amdhsa_next_free_vgpr 256
		.amdhsa_next_free_sgpr 98
		.amdhsa_accum_offset 256
		.amdhsa_reserve_vcc 1
		.amdhsa_float_round_mode_32 0
		.amdhsa_float_round_mode_16_64 0
		.amdhsa_float_denorm_mode_32 3
		.amdhsa_float_denorm_mode_16_64 3
		.amdhsa_dx10_clamp 1
		.amdhsa_ieee_mode 1
		.amdhsa_fp16_overflow 0
		.amdhsa_tg_split 0
		.amdhsa_exception_fp_ieee_invalid_op 0
		.amdhsa_exception_fp_denorm_src 0
		.amdhsa_exception_fp_ieee_div_zero 0
		.amdhsa_exception_fp_ieee_overflow 0
		.amdhsa_exception_fp_ieee_underflow 0
		.amdhsa_exception_fp_ieee_inexact 0
		.amdhsa_exception_int_div_zero 0
	.end_amdhsa_kernel

amdhsa.kernels:
  - .agpr_count:     0
    .args:
      - .offset:         0
        .size:           160
        .value_kind:     by_value
      - .offset:         160
        .size:           4
        .value_kind:     hidden_block_count_x
      - .offset:         164
        .size:           4
        .value_kind:     hidden_block_count_y
      - .offset:         168
        .size:           4
        .value_kind:     hidden_block_count_z
      - .offset:         172
        .size:           2
        .value_kind:     hidden_group_size_x
      - .offset:         174
        .size:           2
        .value_kind:     hidden_group_size_y
      - .offset:         176
        .size:           2
        .value_kind:     hidden_group_size_z
      - .offset:         178
        .size:           2
        .value_kind:     hidden_remainder_x
      - .offset:         180
        .size:           2
        .value_kind:     hidden_remainder_y
      - .offset:         182
        .size:           2
        .value_kind:     hidden_remainder_z
      - .offset:         200
        .size:           8
        .value_kind:     hidden_global_offset_x
      - .offset:         208
        .size:           8
        .value_kind:     hidden_global_offset_y
      - .offset:         216
        .size:           8
        .value_kind:     hidden_global_offset_z
      - .offset:         224
        .size:           2
        .value_kind:     hidden_grid_dims
      - .offset:         248
        .size:           8
        .value_kind:     hidden_multigrid_sync_arg
    .group_segment_fixed_size: 73760
    .kernarg_segment_align: 8
    .kernarg_segment_size: 416
    .language:       OpenCL C
    .language_version:
      - 2
      - 0
    .max_flat_workgroup_size: 256
    .name:           _Z10fwd_kernel6Params
    .private_segment_fixed_size: 0
    .sgpr_count:     104
    .sgpr_spill_count: 171
    .symbol:         _Z10fwd_kernel6Params.kd
    .uniform_work_group_size: 1
    .uses_dynamic_stack: false
    .vgpr_count:     256
    .vgpr_spill_count: 0
    .wavefront_size: 64
